# stack of small exact edits on top of the best version: DPP reductions in prep B, zero attn block skipped and prefetch distance 2 in the scan, loop-invariant norm-weight loads hoisted out of the POST g
# speedup vs baseline: 1.0129x; 1.0021x over previous
.Lscan_O_path:
	v_lshlrev_b32_e32 v2, 4, v14
	s_cmp_lt_u32 s12, 2
	s_cbranch_scc1 .Lscan_P_path
	global_load_dwordx4 v[72:75], v1, s[0:1]
	global_load_dwordx4 v[76:79], v1, s[0:1] offset:1024
	global_load_dwordx4 v[80:83], v1, s[0:1] offset:2048
	global_load_dwordx4 v[84:87], v1, s[0:1] offset:3072
	global_load_dwordx4 v[88:91], v2, s[2:3]
	global_load_dwordx4 v[92:95], v2, s[2:3] offset:1024
	global_load_dwordx4 v[96:99], v1, s[4:5]
	global_load_dwordx4 v[100:103], v1, s[4:5] offset:1024
	global_load_dword v184, v3, s[6:7]
	v_add_u32_e32 v1, 0x4000, v1
	v_add_u32_e32 v2, 0x2000, v2
	v_add_u32_e32 v3, 4, v3
	global_load_dwordx4 v[104:107], v1, s[0:1]
	global_load_dwordx4 v[108:111], v1, s[0:1] offset:1024
	global_load_dwordx4 v[112:115], v1, s[0:1] offset:2048
	global_load_dwordx4 v[116:119], v1, s[0:1] offset:3072
	global_load_dwordx4 v[120:123], v2, s[2:3]
	global_load_dwordx4 v[124:127], v2, s[2:3] offset:1024
	global_load_dwordx4 v[128:131], v1, s[4:5]
	global_load_dwordx4 v[132:135], v1, s[4:5] offset:1024
	global_load_dword v185, v3, s[6:7]
	v_add_u32_e32 v1, 0x4000, v1
	v_add_u32_e32 v2, 0x2000, v2
	v_add_u32_e32 v3, 4, v3
	s_waitcnt vmcnt(0)
	s_movk_i32 s10, 32
.Lscan_O_loop:
	s_waitcnt vmcnt(16)
	ds_read_b128 v[32:35], v8 offset:0
	ds_read_b128 v[36:39], v8 offset:4352
	ds_read_b128 v[40:43], v8 offset:64
	ds_read_b128 v[44:47], v8 offset:4416
	ds_read_b128 v[48:51], v8 offset:128
	ds_read_b128 v[52:55], v8 offset:4480
	ds_read_b128 v[56:59], v8 offset:192
	ds_read_b128 v[60:63], v8 offset:4544
	global_load_dwordx4 v[136:139], v1, s[0:1]
	global_load_dwordx4 v[140:143], v1, s[0:1] offset:1024
	s_waitcnt vmcnt(13)
	v_mul_f32_e32 v16, v184, v16
	v_mul_f32_e32 v17, v184, v17
	v_mul_f32_e32 v18, v184, v18
	v_mul_f32_e32 v19, v184, v19
	global_load_dwordx4 v[144:147], v1, s[0:1] offset:2048
	v_mul_f32_e32 v20, v184, v20
	v_mul_f32_e32 v21, v184, v21
	v_mul_f32_e32 v22, v184, v22
	v_mul_f32_e32 v23, v184, v23
	global_load_dwordx4 v[148:151], v1, s[0:1] offset:3072
	s_waitcnt lgkmcnt(6)
	v_mfma_f32_16x16x32_bf16 v[24:27], v[72:75], v[32:35], 0
	v_mfma_f32_16x16x32_bf16 v[28:31], v[72:75], v[36:39], 0
	global_load_dwordx4 v[188:191], v2, s[2:3]
	s_waitcnt lgkmcnt(4)
	v_mfma_f32_16x16x32_bf16 v[24:27], v[76:79], v[40:43], v[24:27]
	v_mfma_f32_16x16x32_bf16 v[28:31], v[76:79], v[44:47], v[28:31]
	global_load_dwordx4 v[192:195], v2, s[2:3] offset:1024
	s_waitcnt lgkmcnt(2)
	v_mfma_f32_16x16x32_bf16 v[24:27], v[80:83], v[48:51], v[24:27]
	v_mfma_f32_16x16x32_bf16 v[28:31], v[80:83], v[52:55], v[28:31]
	global_load_dwordx4 v[196:199], v1, s[4:5]
	s_waitcnt lgkmcnt(0)
	v_mfma_f32_16x16x32_bf16 v[24:27], v[84:87], v[56:59], v[24:27]
	v_mfma_f32_16x16x32_bf16 v[28:31], v[84:87], v[60:63], v[28:31]
	global_load_dwordx4 v[200:203], v1, s[4:5] offset:1024
	global_load_dword v186, v3, s[6:7]
	v_add_u32_e32 v1, 0x4000, v1
	v_add_u32_e32 v2, 0x2000, v2
	v_add_u32_e32 v3, 4, v3
	s_waitcnt lgkmcnt(0)
	s_barrier
	ds_read_b128 v[32:35], v9 offset:17408
	ds_read_b128 v[36:39], v9 offset:19712
	ds_read_b128 v[40:43], v9 offset:17472
	ds_read_b128 v[44:47], v9 offset:19776
	s_waitcnt lgkmcnt(2)
	v_mfma_f32_16x16x32_bf16 v[16:19], v[96:99], v[32:35], v[16:19]
	v_mfma_f32_16x16x32_bf16 v[20:23], v[96:99], v[36:39], v[20:23]
	v_mfma_f32_16x16x32_bf16 v[24:27], v[88:91], v[32:35], v[24:27]
	v_mfma_f32_16x16x32_bf16 v[28:31], v[88:91], v[36:39], v[28:31]
	s_waitcnt lgkmcnt(0)
	v_mfma_f32_16x16x32_bf16 v[16:19], v[100:103], v[40:43], v[16:19]
	v_mfma_f32_16x16x32_bf16 v[20:23], v[100:103], v[44:47], v[20:23]
	v_mfma_f32_16x16x32_bf16 v[24:27], v[92:95], v[40:43], v[24:27]
	v_mfma_f32_16x16x32_bf16 v[28:31], v[92:95], v[44:47], v[28:31]
	s_nop 5
	v_cvt_pk_bf16_f32 v64, v16, v17
	v_cvt_pk_bf16_f32 v65, v18, v19
	v_cvt_pk_bf16_f32 v66, v20, v21
	v_cvt_pk_bf16_f32 v67, v22, v23
	ds_write_b64 v11, v[64:65] offset:8704
	ds_write_b64 v11, v[66:67] offset:13056
	v_cvt_pk_bf16_f32 v68, v24, v25
	v_cvt_pk_bf16_f32 v69, v26, v27
	v_cvt_pk_bf16_f32 v70, v28, v29
	v_cvt_pk_bf16_f32 v71, v30, v31
	ds_write_b16 v13, v68 offset:0
	ds_write_b16_d16_hi v13, v68 offset:80
	ds_write_b16 v13, v69 offset:160
	ds_write_b16_d16_hi v13, v69 offset:240
	ds_write_b16 v13, v70 offset:32
	ds_write_b16_d16_hi v13, v70 offset:112
	ds_write_b16 v13, v71 offset:192
	ds_write_b16_d16_hi v13, v71 offset:272
	ds_read_b128 v[176:179], v172
	s_waitcnt lgkmcnt(0)
	s_barrier
	global_store_dwordx4 v12, v[176:179], s[8:9]
	v_add_u32_e32 v12, 0x20000, v12
	s_waitcnt vmcnt(16)
	ds_read_b128 v[32:35], v8 offset:8704
	ds_read_b128 v[36:39], v8 offset:13056
	ds_read_b128 v[40:43], v8 offset:8768
	ds_read_b128 v[44:47], v8 offset:13120
	ds_read_b128 v[48:51], v8 offset:8832
	ds_read_b128 v[52:55], v8 offset:13184
	ds_read_b128 v[56:59], v8 offset:8896
	ds_read_b128 v[60:63], v8 offset:13248
	global_load_dwordx4 v[216:219], v1, s[0:1]
	global_load_dwordx4 v[220:223], v1, s[0:1] offset:1024
	s_waitcnt vmcnt(13)
	v_mul_f32_e32 v16, v185, v16
	v_mul_f32_e32 v17, v185, v17
	v_mul_f32_e32 v18, v185, v18
	v_mul_f32_e32 v19, v185, v19
	global_load_dwordx4 v[224:227], v1, s[0:1] offset:2048
	v_mul_f32_e32 v20, v185, v20
	v_mul_f32_e32 v21, v185, v21
	v_mul_f32_e32 v22, v185, v22
	v_mul_f32_e32 v23, v185, v23
	global_load_dwordx4 v[228:231], v1, s[0:1] offset:3072
	s_waitcnt lgkmcnt(6)
	v_mfma_f32_16x16x32_bf16 v[24:27], v[104:107], v[32:35], 0
	v_mfma_f32_16x16x32_bf16 v[28:31], v[104:107], v[36:39], 0
	global_load_dwordx4 v[232:235], v2, s[2:3]
	s_waitcnt lgkmcnt(4)
	v_mfma_f32_16x16x32_bf16 v[24:27], v[108:111], v[40:43], v[24:27]
	v_mfma_f32_16x16x32_bf16 v[28:31], v[108:111], v[44:47], v[28:31]
	global_load_dwordx4 v[236:239], v2, s[2:3] offset:1024
	s_waitcnt lgkmcnt(2)
	v_mfma_f32_16x16x32_bf16 v[24:27], v[112:115], v[48:51], v[24:27]
	v_mfma_f32_16x16x32_bf16 v[28:31], v[112:115], v[52:55], v[28:31]
	global_load_dwordx4 v[240:243], v1, s[4:5]
	s_waitcnt lgkmcnt(0)
	v_mfma_f32_16x16x32_bf16 v[24:27], v[116:119], v[56:59], v[24:27]
	v_mfma_f32_16x16x32_bf16 v[28:31], v[116:119], v[60:63], v[28:31]
	global_load_dwordx4 v[244:247], v1, s[4:5] offset:1024
	global_load_dword v187, v3, s[6:7]
	v_add_u32_e32 v1, 0x4000, v1
	v_add_u32_e32 v2, 0x2000, v2
	v_add_u32_e32 v3, 4, v3
	s_waitcnt lgkmcnt(0)
	s_barrier
	ds_read_b128 v[32:35], v9 offset:17408
	ds_read_b128 v[36:39], v9 offset:19712
	ds_read_b128 v[40:43], v9 offset:17472
	ds_read_b128 v[44:47], v9 offset:19776
	s_waitcnt lgkmcnt(2)
	v_mfma_f32_16x16x32_bf16 v[16:19], v[128:131], v[32:35], v[16:19]
	v_mfma_f32_16x16x32_bf16 v[20:23], v[128:131], v[36:39], v[20:23]
	v_mfma_f32_16x16x32_bf16 v[24:27], v[120:123], v[32:35], v[24:27]
	v_mfma_f32_16x16x32_bf16 v[28:31], v[120:123], v[36:39], v[28:31]
	s_waitcnt lgkmcnt(0)
	v_mfma_f32_16x16x32_bf16 v[16:19], v[132:135], v[40:43], v[16:19]
	v_mfma_f32_16x16x32_bf16 v[20:23], v[132:135], v[44:47], v[20:23]
	v_mfma_f32_16x16x32_bf16 v[24:27], v[124:127], v[40:43], v[24:27]
	v_mfma_f32_16x16x32_bf16 v[28:31], v[124:127], v[44:47], v[28:31]
	s_nop 5
	v_cvt_pk_bf16_f32 v64, v16, v17
	v_cvt_pk_bf16_f32 v65, v18, v19
	v_cvt_pk_bf16_f32 v66, v20, v21
	v_cvt_pk_bf16_f32 v67, v22, v23
	ds_write_b64 v11, v[64:65] offset:0
	ds_write_b64 v11, v[66:67] offset:4352
	v_cvt_pk_bf16_f32 v68, v24, v25
	v_cvt_pk_bf16_f32 v69, v26, v27
	v_cvt_pk_bf16_f32 v70, v28, v29
	v_cvt_pk_bf16_f32 v71, v30, v31
	ds_write_b16 v13, v68 offset:0
	ds_write_b16_d16_hi v13, v68 offset:80
	ds_write_b16 v13, v69 offset:160
	ds_write_b16_d16_hi v13, v69 offset:240
	ds_write_b16 v13, v70 offset:32
	ds_write_b16_d16_hi v13, v70 offset:112
	ds_write_b16 v13, v71 offset:192
	ds_write_b16_d16_hi v13, v71 offset:272
	ds_read_b128 v[176:179], v172
	s_waitcnt lgkmcnt(0)
	s_barrier
	global_store_dwordx4 v12, v[176:179], s[8:9]
	v_add_u32_e32 v12, 0x20000, v12
	s_waitcnt vmcnt(16)
	ds_read_b128 v[32:35], v8 offset:0
	ds_read_b128 v[36:39], v8 offset:4352
	ds_read_b128 v[40:43], v8 offset:64
	ds_read_b128 v[44:47], v8 offset:4416
	ds_read_b128 v[48:51], v8 offset:128
	ds_read_b128 v[52:55], v8 offset:4480
	ds_read_b128 v[56:59], v8 offset:192
	ds_read_b128 v[60:63], v8 offset:4544
	global_load_dwordx4 v[72:75], v1, s[0:1]
	global_load_dwordx4 v[76:79], v1, s[0:1] offset:1024
	s_waitcnt vmcnt(13)
	v_mul_f32_e32 v16, v186, v16
	v_mul_f32_e32 v17, v186, v17
	v_mul_f32_e32 v18, v186, v18
	v_mul_f32_e32 v19, v186, v19
	global_load_dwordx4 v[80:83], v1, s[0:1] offset:2048
	v_mul_f32_e32 v20, v186, v20
	v_mul_f32_e32 v21, v186, v21
	v_mul_f32_e32 v22, v186, v22
	v_mul_f32_e32 v23, v186, v23
	global_load_dwordx4 v[84:87], v1, s[0:1] offset:3072
	s_waitcnt lgkmcnt(6)
	v_mfma_f32_16x16x32_bf16 v[24:27], v[136:139], v[32:35], 0
	v_mfma_f32_16x16x32_bf16 v[28:31], v[136:139], v[36:39], 0
	global_load_dwordx4 v[88:91], v2, s[2:3]
	s_waitcnt lgkmcnt(4)
	v_mfma_f32_16x16x32_bf16 v[24:27], v[140:143], v[40:43], v[24:27]
	v_mfma_f32_16x16x32_bf16 v[28:31], v[140:143], v[44:47], v[28:31]
	global_load_dwordx4 v[92:95], v2, s[2:3] offset:1024
	s_waitcnt lgkmcnt(2)
	v_mfma_f32_16x16x32_bf16 v[24:27], v[144:147], v[48:51], v[24:27]
	v_mfma_f32_16x16x32_bf16 v[28:31], v[144:147], v[52:55], v[28:31]
	global_load_dwordx4 v[96:99], v1, s[4:5]
	s_waitcnt lgkmcnt(0)
	v_mfma_f32_16x16x32_bf16 v[24:27], v[148:151], v[56:59], v[24:27]
	v_mfma_f32_16x16x32_bf16 v[28:31], v[148:151], v[60:63], v[28:31]
	global_load_dwordx4 v[100:103], v1, s[4:5] offset:1024
	global_load_dword v184, v3, s[6:7]
	v_add_u32_e32 v1, 0x4000, v1
	v_add_u32_e32 v2, 0x2000, v2
	v_add_u32_e32 v3, 4, v3
	s_waitcnt lgkmcnt(0)
	s_barrier
	ds_read_b128 v[32:35], v9 offset:17408
	ds_read_b128 v[36:39], v9 offset:19712
	ds_read_b128 v[40:43], v9 offset:17472
	ds_read_b128 v[44:47], v9 offset:19776
	s_waitcnt lgkmcnt(2)
	v_mfma_f32_16x16x32_bf16 v[16:19], v[196:199], v[32:35], v[16:19]
	v_mfma_f32_16x16x32_bf16 v[20:23], v[196:199], v[36:39], v[20:23]
	v_mfma_f32_16x16x32_bf16 v[24:27], v[188:191], v[32:35], v[24:27]
	v_mfma_f32_16x16x32_bf16 v[28:31], v[188:191], v[36:39], v[28:31]
	s_waitcnt lgkmcnt(0)
	v_mfma_f32_16x16x32_bf16 v[16:19], v[200:203], v[40:43], v[16:19]
	v_mfma_f32_16x16x32_bf16 v[20:23], v[200:203], v[44:47], v[20:23]
	v_mfma_f32_16x16x32_bf16 v[24:27], v[192:195], v[40:43], v[24:27]
	v_mfma_f32_16x16x32_bf16 v[28:31], v[192:195], v[44:47], v[28:31]
	s_nop 5
	v_cvt_pk_bf16_f32 v64, v16, v17
	v_cvt_pk_bf16_f32 v65, v18, v19
	v_cvt_pk_bf16_f32 v66, v20, v21
	v_cvt_pk_bf16_f32 v67, v22, v23
	ds_write_b64 v11, v[64:65] offset:8704
	ds_write_b64 v11, v[66:67] offset:13056
	v_cvt_pk_bf16_f32 v68, v24, v25
	v_cvt_pk_bf16_f32 v69, v26, v27
	v_cvt_pk_bf16_f32 v70, v28, v29
	v_cvt_pk_bf16_f32 v71, v30, v31
	ds_write_b16 v13, v68 offset:0
	ds_write_b16_d16_hi v13, v68 offset:80
	ds_write_b16 v13, v69 offset:160
	ds_write_b16_d16_hi v13, v69 offset:240
	ds_write_b16 v13, v70 offset:32
	ds_write_b16_d16_hi v13, v70 offset:112
	ds_write_b16 v13, v71 offset:192
	ds_write_b16_d16_hi v13, v71 offset:272
	ds_read_b128 v[176:179], v172
	s_waitcnt lgkmcnt(0)
	s_barrier
	global_store_dwordx4 v12, v[176:179], s[8:9]
	v_add_u32_e32 v12, 0x20000, v12
	s_waitcnt vmcnt(16)
	ds_read_b128 v[32:35], v8 offset:8704
	ds_read_b128 v[36:39], v8 offset:13056
	ds_read_b128 v[40:43], v8 offset:8768
	ds_read_b128 v[44:47], v8 offset:13120
	ds_read_b128 v[48:51], v8 offset:8832
	ds_read_b128 v[52:55], v8 offset:13184
	ds_read_b128 v[56:59], v8 offset:8896
	ds_read_b128 v[60:63], v8 offset:13248
	global_load_dwordx4 v[104:107], v1, s[0:1]
	global_load_dwordx4 v[108:111], v1, s[0:1] offset:1024
	s_waitcnt vmcnt(13)
	v_mul_f32_e32 v16, v187, v16
	v_mul_f32_e32 v17, v187, v17
	v_mul_f32_e32 v18, v187, v18
	v_mul_f32_e32 v19, v187, v19
	global_load_dwordx4 v[112:115], v1, s[0:1] offset:2048
	v_mul_f32_e32 v20, v187, v20
	v_mul_f32_e32 v21, v187, v21
	v_mul_f32_e32 v22, v187, v22
	v_mul_f32_e32 v23, v187, v23
	global_load_dwordx4 v[116:119], v1, s[0:1] offset:3072
	s_waitcnt lgkmcnt(6)
	v_mfma_f32_16x16x32_bf16 v[24:27], v[216:219], v[32:35], 0
	v_mfma_f32_16x16x32_bf16 v[28:31], v[216:219], v[36:39], 0
	global_load_dwordx4 v[120:123], v2, s[2:3]
	s_waitcnt lgkmcnt(4)
	v_mfma_f32_16x16x32_bf16 v[24:27], v[220:223], v[40:43], v[24:27]
	v_mfma_f32_16x16x32_bf16 v[28:31], v[220:223], v[44:47], v[28:31]
	global_load_dwordx4 v[124:127], v2, s[2:3] offset:1024
	s_waitcnt lgkmcnt(2)
	v_mfma_f32_16x16x32_bf16 v[24:27], v[224:227], v[48:51], v[24:27]
	v_mfma_f32_16x16x32_bf16 v[28:31], v[224:227], v[52:55], v[28:31]
	global_load_dwordx4 v[128:131], v1, s[4:5]
	s_waitcnt lgkmcnt(0)
	v_mfma_f32_16x16x32_bf16 v[24:27], v[228:231], v[56:59], v[24:27]
	v_mfma_f32_16x16x32_bf16 v[28:31], v[228:231], v[60:63], v[28:31]
	global_load_dwordx4 v[132:135], v1, s[4:5] offset:1024
	global_load_dword v185, v3, s[6:7]
	v_add_u32_e32 v1, 0x4000, v1
	v_add_u32_e32 v2, 0x2000, v2
	v_add_u32_e32 v3, 4, v3
	s_waitcnt lgkmcnt(0)
	s_barrier
	ds_read_b128 v[32:35], v9 offset:17408
	ds_read_b128 v[36:39], v9 offset:19712
	ds_read_b128 v[40:43], v9 offset:17472
	ds_read_b128 v[44:47], v9 offset:19776
	s_waitcnt lgkmcnt(2)
	v_mfma_f32_16x16x32_bf16 v[16:19], v[240:243], v[32:35], v[16:19]
	v_mfma_f32_16x16x32_bf16 v[20:23], v[240:243], v[36:39], v[20:23]
	v_mfma_f32_16x16x32_bf16 v[24:27], v[232:235], v[32:35], v[24:27]
	v_mfma_f32_16x16x32_bf16 v[28:31], v[232:235], v[36:39], v[28:31]
	s_waitcnt lgkmcnt(0)
	v_mfma_f32_16x16x32_bf16 v[16:19], v[244:247], v[40:43], v[16:19]
	v_mfma_f32_16x16x32_bf16 v[20:23], v[244:247], v[44:47], v[20:23]
	v_mfma_f32_16x16x32_bf16 v[24:27], v[236:239], v[40:43], v[24:27]
	v_mfma_f32_16x16x32_bf16 v[28:31], v[236:239], v[44:47], v[28:31]
	s_nop 5
	v_cvt_pk_bf16_f32 v64, v16, v17
	v_cvt_pk_bf16_f32 v65, v18, v19
	v_cvt_pk_bf16_f32 v66, v20, v21
	v_cvt_pk_bf16_f32 v67, v22, v23
	ds_write_b64 v11, v[64:65] offset:0
	ds_write_b64 v11, v[66:67] offset:4352
	v_cvt_pk_bf16_f32 v68, v24, v25
	v_cvt_pk_bf16_f32 v69, v26, v27
	v_cvt_pk_bf16_f32 v70, v28, v29
	v_cvt_pk_bf16_f32 v71, v30, v31
	ds_write_b16 v13, v68 offset:0
	ds_write_b16_d16_hi v13, v68 offset:80
	ds_write_b16 v13, v69 offset:160
	ds_write_b16_d16_hi v13, v69 offset:240
	ds_write_b16 v13, v70 offset:32
	ds_write_b16_d16_hi v13, v70 offset:112
	ds_write_b16 v13, v71 offset:192
	ds_write_b16_d16_hi v13, v71 offset:272
	ds_read_b128 v[176:179], v172
	s_waitcnt lgkmcnt(0)
	s_barrier
	global_store_dwordx4 v12, v[176:179], s[8:9]
	v_add_u32_e32 v12, 0x20000, v12
	s_sub_u32 s10, s10, 1
	s_cmp_lg_u32 s10, 0
	s_cbranch_scc1 .Lscan_O_loop
	s_branch .Lscan_done
.Lscan_P_path:
	global_load_dwordx4 v[72:75], v1, s[0:1]
	global_load_dwordx4 v[76:79], v1, s[0:1] offset:1024
	global_load_dwordx4 v[80:83], v1, s[0:1] offset:2048
	global_load_dwordx4 v[84:87], v1, s[0:1] offset:3072
	global_load_dwordx4 v[88:91], v2, s[2:3]
	global_load_dwordx4 v[96:99], v1, s[4:5]
	global_load_dwordx4 v[100:103], v1, s[4:5] offset:1024
	global_load_dword v184, v3, s[6:7]
	v_add_u32_e32 v1, 0x4000, v1
	v_add_u32_e32 v2, 0x2000, v2
	v_add_u32_e32 v3, 4, v3
	global_load_dwordx4 v[104:107], v1, s[0:1]
	global_load_dwordx4 v[108:111], v1, s[0:1] offset:1024
	global_load_dwordx4 v[112:115], v1, s[0:1] offset:2048
	global_load_dwordx4 v[116:119], v1, s[0:1] offset:3072
	global_load_dwordx4 v[120:123], v2, s[2:3]
	global_load_dwordx4 v[128:131], v1, s[4:5]
	global_load_dwordx4 v[132:135], v1, s[4:5] offset:1024
	global_load_dword v185, v3, s[6:7]
	v_add_u32_e32 v1, 0x4000, v1
	v_add_u32_e32 v2, 0x2000, v2
	v_add_u32_e32 v3, 4, v3
	s_waitcnt vmcnt(0)
	s_movk_i32 s10, 32
.Lscan_P_loop:
	s_waitcnt vmcnt(14)
	ds_read_b128 v[32:35], v8 offset:0
	ds_read_b128 v[36:39], v8 offset:4352
	ds_read_b128 v[40:43], v8 offset:64
	ds_read_b128 v[44:47], v8 offset:4416
	ds_read_b128 v[48:51], v8 offset:128
	ds_read_b128 v[52:55], v8 offset:4480
	ds_read_b128 v[56:59], v8 offset:192
	ds_read_b128 v[60:63], v8 offset:4544
	global_load_dwordx4 v[136:139], v1, s[0:1]
	global_load_dwordx4 v[140:143], v1, s[0:1] offset:1024
	s_waitcnt vmcnt(12)
	v_mul_f32_e32 v16, v184, v16
	v_mul_f32_e32 v17, v184, v17
	v_mul_f32_e32 v18, v184, v18
	v_mul_f32_e32 v19, v184, v19
	global_load_dwordx4 v[144:147], v1, s[0:1] offset:2048
	v_mul_f32_e32 v20, v184, v20
	v_mul_f32_e32 v21, v184, v21
	v_mul_f32_e32 v22, v184, v22
	v_mul_f32_e32 v23, v184, v23
	global_load_dwordx4 v[148:151], v1, s[0:1] offset:3072
	s_waitcnt lgkmcnt(6)
	v_mfma_f32_16x16x32_bf16 v[24:27], v[72:75], v[32:35], 0
	v_mfma_f32_16x16x32_bf16 v[28:31], v[72:75], v[36:39], 0
	global_load_dwordx4 v[188:191], v2, s[2:3]
	s_waitcnt lgkmcnt(4)
	v_mfma_f32_16x16x32_bf16 v[24:27], v[76:79], v[40:43], v[24:27]
	v_mfma_f32_16x16x32_bf16 v[28:31], v[76:79], v[44:47], v[28:31]
	global_load_dwordx4 v[196:199], v1, s[4:5]
	s_waitcnt lgkmcnt(2)
	v_mfma_f32_16x16x32_bf16 v[24:27], v[80:83], v[48:51], v[24:27]
	v_mfma_f32_16x16x32_bf16 v[28:31], v[80:83], v[52:55], v[28:31]
	global_load_dwordx4 v[200:203], v1, s[4:5] offset:1024
	s_waitcnt lgkmcnt(0)
	v_mfma_f32_16x16x32_bf16 v[24:27], v[84:87], v[56:59], v[24:27]
	v_mfma_f32_16x16x32_bf16 v[28:31], v[84:87], v[60:63], v[28:31]
	global_load_dword v186, v3, s[6:7]
	v_add_u32_e32 v1, 0x4000, v1
	v_add_u32_e32 v2, 0x2000, v2
	v_add_u32_e32 v3, 4, v3
	s_waitcnt lgkmcnt(0)
	s_barrier
	ds_read_b128 v[32:35], v9 offset:17408
	ds_read_b128 v[36:39], v9 offset:19712
	ds_read_b128 v[40:43], v9 offset:17472
	ds_read_b128 v[44:47], v9 offset:19776
	s_waitcnt lgkmcnt(2)
	v_mfma_f32_16x16x32_bf16 v[16:19], v[96:99], v[32:35], v[16:19]
	v_mfma_f32_16x16x32_bf16 v[20:23], v[96:99], v[36:39], v[20:23]
	v_mfma_f32_16x16x32_bf16 v[24:27], v[88:91], v[32:35], v[24:27]
	v_mfma_f32_16x16x32_bf16 v[28:31], v[88:91], v[36:39], v[28:31]
	s_waitcnt lgkmcnt(0)
	v_mfma_f32_16x16x32_bf16 v[16:19], v[100:103], v[40:43], v[16:19]
	v_mfma_f32_16x16x32_bf16 v[20:23], v[100:103], v[44:47], v[20:23]
	s_nop 7
	v_cvt_pk_bf16_f32 v64, v16, v17
	v_cvt_pk_bf16_f32 v65, v18, v19
	v_cvt_pk_bf16_f32 v66, v20, v21
	v_cvt_pk_bf16_f32 v67, v22, v23
	ds_write_b64 v11, v[64:65] offset:8704
	ds_write_b64 v11, v[66:67] offset:13056
	v_cvt_pk_bf16_f32 v68, v24, v25
	v_cvt_pk_bf16_f32 v69, v26, v27
	v_cvt_pk_bf16_f32 v70, v28, v29
	v_cvt_pk_bf16_f32 v71, v30, v31
	ds_write_b16 v13, v68 offset:0
	ds_write_b16_d16_hi v13, v68 offset:80
	ds_write_b16 v13, v69 offset:160
	ds_write_b16_d16_hi v13, v69 offset:240
	ds_write_b16 v13, v70 offset:32
	ds_write_b16_d16_hi v13, v70 offset:112
	ds_write_b16 v13, v71 offset:192
	ds_write_b16_d16_hi v13, v71 offset:272
	ds_read_b128 v[176:179], v172
	s_waitcnt lgkmcnt(0)
	s_barrier
	global_store_dwordx4 v12, v[176:179], s[8:9]
	v_add_u32_e32 v12, 0x20000, v12
	s_waitcnt vmcnt(14)
	ds_read_b128 v[32:35], v8 offset:8704
	ds_read_b128 v[36:39], v8 offset:13056
	ds_read_b128 v[40:43], v8 offset:8768
	ds_read_b128 v[44:47], v8 offset:13120
	ds_read_b128 v[48:51], v8 offset:8832
	ds_read_b128 v[52:55], v8 offset:13184
	ds_read_b128 v[56:59], v8 offset:8896
	ds_read_b128 v[60:63], v8 offset:13248
	global_load_dwordx4 v[216:219], v1, s[0:1]
	global_load_dwordx4 v[220:223], v1, s[0:1] offset:1024
	s_waitcnt vmcnt(12)
	v_mul_f32_e32 v16, v185, v16
	v_mul_f32_e32 v17, v185, v17
	v_mul_f32_e32 v18, v185, v18
	v_mul_f32_e32 v19, v185, v19
	global_load_dwordx4 v[224:227], v1, s[0:1] offset:2048
	v_mul_f32_e32 v20, v185, v20
	v_mul_f32_e32 v21, v185, v21
	v_mul_f32_e32 v22, v185, v22
	v_mul_f32_e32 v23, v185, v23
	global_load_dwordx4 v[228:231], v1, s[0:1] offset:3072
	s_waitcnt lgkmcnt(6)
	v_mfma_f32_16x16x32_bf16 v[24:27], v[104:107], v[32:35], 0
	v_mfma_f32_16x16x32_bf16 v[28:31], v[104:107], v[36:39], 0
	global_load_dwordx4 v[232:235], v2, s[2:3]
	s_waitcnt lgkmcnt(4)
	v_mfma_f32_16x16x32_bf16 v[24:27], v[108:111], v[40:43], v[24:27]
	v_mfma_f32_16x16x32_bf16 v[28:31], v[108:111], v[44:47], v[28:31]
	global_load_dwordx4 v[240:243], v1, s[4:5]
	s_waitcnt lgkmcnt(2)
	v_mfma_f32_16x16x32_bf16 v[24:27], v[112:115], v[48:51], v[24:27]
	v_mfma_f32_16x16x32_bf16 v[28:31], v[112:115], v[52:55], v[28:31]
	global_load_dwordx4 v[244:247], v1, s[4:5] offset:1024
	s_waitcnt lgkmcnt(0)
	v_mfma_f32_16x16x32_bf16 v[24:27], v[116:119], v[56:59], v[24:27]
	v_mfma_f32_16x16x32_bf16 v[28:31], v[116:119], v[60:63], v[28:31]
	global_load_dword v187, v3, s[6:7]
	v_add_u32_e32 v1, 0x4000, v1
	v_add_u32_e32 v2, 0x2000, v2
	v_add_u32_e32 v3, 4, v3
	s_waitcnt lgkmcnt(0)
	s_barrier
	ds_read_b128 v[32:35], v9 offset:17408
	ds_read_b128 v[36:39], v9 offset:19712
	ds_read_b128 v[40:43], v9 offset:17472
	ds_read_b128 v[44:47], v9 offset:19776
	s_waitcnt lgkmcnt(2)
	v_mfma_f32_16x16x32_bf16 v[16:19], v[128:131], v[32:35], v[16:19]
	v_mfma_f32_16x16x32_bf16 v[20:23], v[128:131], v[36:39], v[20:23]
	v_mfma_f32_16x16x32_bf16 v[24:27], v[120:123], v[32:35], v[24:27]
	v_mfma_f32_16x16x32_bf16 v[28:31], v[120:123], v[36:39], v[28:31]
	s_waitcnt lgkmcnt(0)
	v_mfma_f32_16x16x32_bf16 v[16:19], v[132:135], v[40:43], v[16:19]
	v_mfma_f32_16x16x32_bf16 v[20:23], v[132:135], v[44:47], v[20:23]
	s_nop 7
	v_cvt_pk_bf16_f32 v64, v16, v17
	v_cvt_pk_bf16_f32 v65, v18, v19
	v_cvt_pk_bf16_f32 v66, v20, v21
	v_cvt_pk_bf16_f32 v67, v22, v23
	ds_write_b64 v11, v[64:65] offset:0
	ds_write_b64 v11, v[66:67] offset:4352
	v_cvt_pk_bf16_f32 v68, v24, v25
	v_cvt_pk_bf16_f32 v69, v26, v27
	v_cvt_pk_bf16_f32 v70, v28, v29
	v_cvt_pk_bf16_f32 v71, v30, v31
	ds_write_b16 v13, v68 offset:0
	ds_write_b16_d16_hi v13, v68 offset:80
	ds_write_b16 v13, v69 offset:160
	ds_write_b16_d16_hi v13, v69 offset:240
	ds_write_b16 v13, v70 offset:32
	ds_write_b16_d16_hi v13, v70 offset:112
	ds_write_b16 v13, v71 offset:192
	ds_write_b16_d16_hi v13, v71 offset:272
	ds_read_b128 v[176:179], v172
	s_waitcnt lgkmcnt(0)
	s_barrier
	global_store_dwordx4 v12, v[176:179], s[8:9]
	v_add_u32_e32 v12, 0x20000, v12
	s_waitcnt vmcnt(14)
	ds_read_b128 v[32:35], v8 offset:0
	ds_read_b128 v[36:39], v8 offset:4352
	ds_read_b128 v[40:43], v8 offset:64
	ds_read_b128 v[44:47], v8 offset:4416
	ds_read_b128 v[48:51], v8 offset:128
	ds_read_b128 v[52:55], v8 offset:4480
	ds_read_b128 v[56:59], v8 offset:192
	ds_read_b128 v[60:63], v8 offset:4544
	global_load_dwordx4 v[72:75], v1, s[0:1]
	global_load_dwordx4 v[76:79], v1, s[0:1] offset:1024
	s_waitcnt vmcnt(12)
	v_mul_f32_e32 v16, v186, v16
	v_mul_f32_e32 v17, v186, v17
	v_mul_f32_e32 v18, v186, v18
	v_mul_f32_e32 v19, v186, v19
	global_load_dwordx4 v[80:83], v1, s[0:1] offset:2048
	v_mul_f32_e32 v20, v186, v20
	v_mul_f32_e32 v21, v186, v21
	v_mul_f32_e32 v22, v186, v22
	v_mul_f32_e32 v23, v186, v23
	global_load_dwordx4 v[84:87], v1, s[0:1] offset:3072
	s_waitcnt lgkmcnt(6)
	v_mfma_f32_16x16x32_bf16 v[24:27], v[136:139], v[32:35], 0
	v_mfma_f32_16x16x32_bf16 v[28:31], v[136:139], v[36:39], 0
	global_load_dwordx4 v[88:91], v2, s[2:3]
	s_waitcnt lgkmcnt(4)
	v_mfma_f32_16x16x32_bf16 v[24:27], v[140:143], v[40:43], v[24:27]
	v_mfma_f32_16x16x32_bf16 v[28:31], v[140:143], v[44:47], v[28:31]
	global_load_dwordx4 v[96:99], v1, s[4:5]
	s_waitcnt lgkmcnt(2)
	v_mfma_f32_16x16x32_bf16 v[24:27], v[144:147], v[48:51], v[24:27]
	v_mfma_f32_16x16x32_bf16 v[28:31], v[144:147], v[52:55], v[28:31]
	global_load_dwordx4 v[100:103], v1, s[4:5] offset:1024
	s_waitcnt lgkmcnt(0)
	v_mfma_f32_16x16x32_bf16 v[24:27], v[148:151], v[56:59], v[24:27]
	v_mfma_f32_16x16x32_bf16 v[28:31], v[148:151], v[60:63], v[28:31]
	global_load_dword v184, v3, s[6:7]
	v_add_u32_e32 v1, 0x4000, v1
	v_add_u32_e32 v2, 0x2000, v2
	v_add_u32_e32 v3, 4, v3
	s_waitcnt lgkmcnt(0)
	s_barrier
	ds_read_b128 v[32:35], v9 offset:17408
	ds_read_b128 v[36:39], v9 offset:19712
	ds_read_b128 v[40:43], v9 offset:17472
	ds_read_b128 v[44:47], v9 offset:19776
	s_waitcnt lgkmcnt(2)
	v_mfma_f32_16x16x32_bf16 v[16:19], v[196:199], v[32:35], v[16:19]
	v_mfma_f32_16x16x32_bf16 v[20:23], v[196:199], v[36:39], v[20:23]
	v_mfma_f32_16x16x32_bf16 v[24:27], v[188:191], v[32:35], v[24:27]
	v_mfma_f32_16x16x32_bf16 v[28:31], v[188:191], v[36:39], v[28:31]
	s_waitcnt lgkmcnt(0)
	v_mfma_f32_16x16x32_bf16 v[16:19], v[200:203], v[40:43], v[16:19]
	v_mfma_f32_16x16x32_bf16 v[20:23], v[200:203], v[44:47], v[20:23]
	s_nop 7
	v_cvt_pk_bf16_f32 v64, v16, v17
	v_cvt_pk_bf16_f32 v65, v18, v19
	v_cvt_pk_bf16_f32 v66, v20, v21
	v_cvt_pk_bf16_f32 v67, v22, v23
	ds_write_b64 v11, v[64:65] offset:8704
	ds_write_b64 v11, v[66:67] offset:13056
	v_cvt_pk_bf16_f32 v68, v24, v25
	v_cvt_pk_bf16_f32 v69, v26, v27
	v_cvt_pk_bf16_f32 v70, v28, v29
	v_cvt_pk_bf16_f32 v71, v30, v31
	ds_write_b16 v13, v68 offset:0
	ds_write_b16_d16_hi v13, v68 offset:80
	ds_write_b16 v13, v69 offset:160
	ds_write_b16_d16_hi v13, v69 offset:240
	ds_write_b16 v13, v70 offset:32
	ds_write_b16_d16_hi v13, v70 offset:112
	ds_write_b16 v13, v71 offset:192
	ds_write_b16_d16_hi v13, v71 offset:272
	ds_read_b128 v[176:179], v172
	s_waitcnt lgkmcnt(0)
	s_barrier
	global_store_dwordx4 v12, v[176:179], s[8:9]
	v_add_u32_e32 v12, 0x20000, v12
	s_waitcnt vmcnt(14)
	ds_read_b128 v[32:35], v8 offset:8704
	ds_read_b128 v[36:39], v8 offset:13056
	ds_read_b128 v[40:43], v8 offset:8768
	ds_read_b128 v[44:47], v8 offset:13120
	ds_read_b128 v[48:51], v8 offset:8832
	ds_read_b128 v[52:55], v8 offset:13184
	ds_read_b128 v[56:59], v8 offset:8896
	ds_read_b128 v[60:63], v8 offset:13248
	global_load_dwordx4 v[104:107], v1, s[0:1]
	global_load_dwordx4 v[108:111], v1, s[0:1] offset:1024
	s_waitcnt vmcnt(12)
	v_mul_f32_e32 v16, v187, v16
	v_mul_f32_e32 v17, v187, v17
	v_mul_f32_e32 v18, v187, v18
	v_mul_f32_e32 v19, v187, v19
	global_load_dwordx4 v[112:115], v1, s[0:1] offset:2048
	v_mul_f32_e32 v20, v187, v20
	v_mul_f32_e32 v21, v187, v21
	v_mul_f32_e32 v22, v187, v22
	v_mul_f32_e32 v23, v187, v23
	global_load_dwordx4 v[116:119], v1, s[0:1] offset:3072
	s_waitcnt lgkmcnt(6)
	v_mfma_f32_16x16x32_bf16 v[24:27], v[216:219], v[32:35], 0
	v_mfma_f32_16x16x32_bf16 v[28:31], v[216:219], v[36:39], 0
	global_load_dwordx4 v[120:123], v2, s[2:3]
	s_waitcnt lgkmcnt(4)
	v_mfma_f32_16x16x32_bf16 v[24:27], v[220:223], v[40:43], v[24:27]
	v_mfma_f32_16x16x32_bf16 v[28:31], v[220:223], v[44:47], v[28:31]
	global_load_dwordx4 v[128:131], v1, s[4:5]
	s_waitcnt lgkmcnt(2)
	v_mfma_f32_16x16x32_bf16 v[24:27], v[224:227], v[48:51], v[24:27]
	v_mfma_f32_16x16x32_bf16 v[28:31], v[224:227], v[52:55], v[28:31]
	global_load_dwordx4 v[132:135], v1, s[4:5] offset:1024
	s_waitcnt lgkmcnt(0)
	v_mfma_f32_16x16x32_bf16 v[24:27], v[228:231], v[56:59], v[24:27]
	v_mfma_f32_16x16x32_bf16 v[28:31], v[228:231], v[60:63], v[28:31]
	global_load_dword v185, v3, s[6:7]
	v_add_u32_e32 v1, 0x4000, v1
	v_add_u32_e32 v2, 0x2000, v2
	v_add_u32_e32 v3, 4, v3
	s_waitcnt lgkmcnt(0)
	s_barrier
	ds_read_b128 v[32:35], v9 offset:17408
	ds_read_b128 v[36:39], v9 offset:19712
	ds_read_b128 v[40:43], v9 offset:17472
	ds_read_b128 v[44:47], v9 offset:19776
	s_waitcnt lgkmcnt(2)
	v_mfma_f32_16x16x32_bf16 v[16:19], v[240:243], v[32:35], v[16:19]
	v_mfma_f32_16x16x32_bf16 v[20:23], v[240:243], v[36:39], v[20:23]
	v_mfma_f32_16x16x32_bf16 v[24:27], v[232:235], v[32:35], v[24:27]
	v_mfma_f32_16x16x32_bf16 v[28:31], v[232:235], v[36:39], v[28:31]
	s_waitcnt lgkmcnt(0)
	v_mfma_f32_16x16x32_bf16 v[16:19], v[244:247], v[40:43], v[16:19]
	v_mfma_f32_16x16x32_bf16 v[20:23], v[244:247], v[44:47], v[20:23]
	s_nop 7
	v_cvt_pk_bf16_f32 v64, v16, v17
	v_cvt_pk_bf16_f32 v65, v18, v19
	v_cvt_pk_bf16_f32 v66, v20, v21
	v_cvt_pk_bf16_f32 v67, v22, v23
	ds_write_b64 v11, v[64:65] offset:0
	ds_write_b64 v11, v[66:67] offset:4352
	v_cvt_pk_bf16_f32 v68, v24, v25
	v_cvt_pk_bf16_f32 v69, v26, v27
	v_cvt_pk_bf16_f32 v70, v28, v29
	v_cvt_pk_bf16_f32 v71, v30, v31
	ds_write_b16 v13, v68 offset:0
	ds_write_b16_d16_hi v13, v68 offset:80
	ds_write_b16 v13, v69 offset:160
	ds_write_b16_d16_hi v13, v69 offset:240
	ds_write_b16 v13, v70 offset:32
	ds_write_b16_d16_hi v13, v70 offset:112
	ds_write_b16 v13, v71 offset:192
	ds_write_b16_d16_hi v13, v71 offset:272
	ds_read_b128 v[176:179], v172
	s_waitcnt lgkmcnt(0)
	s_barrier
	global_store_dwordx4 v12, v[176:179], s[8:9]
	v_add_u32_e32 v12, 0x20000, v12
	s_sub_u32 s10, s10, 1
	s_cmp_lg_u32 s10, 0
	s_cbranch_scc1 .Lscan_P_loop

.LBB0_759:
	s_or_b64 exec, exec, s[0:1]
	s_mov_b32 s0, 0x200000
	v_cmp_gt_i32_e32 vcc, s0, v1
	s_and_saveexec_b64 s[0:1], vcc
	v_readlane_b32 s12, v251, 59
	v_readlane_b32 s13, v251, 60
	s_cbranch_execz .LBB0_762
	v_and_b32_e32 v3, 64, v211
	v_xor_b32_e32 v2, 1, v211
	v_add_u32_e32 v9, 64, v3
	s_add_u32 s2, s6, 0xb400000
	v_cmp_lt_i32_e32 vcc, v2, v9
	v_xor_b32_e32 v3, 2, v211
	s_addc_u32 s3, s7, 0
	v_cndmask_b32_e32 v2, v211, v2, vcc
	v_cmp_lt_i32_e32 vcc, v3, v9
	v_xor_b32_e32 v8, 4, v211
	s_add_u32 s4, s6, 0xf400000
	v_cndmask_b32_e32 v3, v211, v3, vcc
	v_cmp_lt_i32_e32 vcc, v8, v9
	v_xor_b32_e32 v10, 8, v211
	s_addc_u32 s5, s7, 0
	v_cndmask_b32_e32 v8, v211, v8, vcc
	v_cmp_lt_i32_e32 vcc, v10, v9
	s_add_u32 s6, s6, 0x13800000
	v_readlane_b32 s8, v251, 1
	v_cndmask_b32_e32 v9, v211, v10, vcc
	s_addc_u32 s7, s7, 0
	v_lshlrev_b32_e32 v2, 2, v2
	v_lshlrev_b32_e32 v3, 2, v3
	v_lshlrev_b32_e32 v8, 2, v8
	v_lshlrev_b32_e32 v9, 2, v9
	v_lshl_add_u32 v10, v12, 3, s8
	s_mov_b64 s[8:9], 0
	v_and_b32_e32 v11, 0x78, v10
	v_lshlrev_b32_e32 v11, 2, v11
	global_load_dwordx4 v[20:23], v11, s[12:13] offset:16
	global_load_dwordx4 v[24:27], v11, s[12:13]
.LBB0_761:
	v_ashrrev_i32_e32 v12, 7, v1
	v_ashrrev_i32_e32 v13, 31, v12
	v_lshlrev_b64 v[28:29], 11, v[12:13]
	v_and_b32_e32 v14, 0x3f8, v10
	v_lshl_add_u64 v[12:13], s[2:3], 0, v[28:29]
	v_lshlrev_b32_e32 v30, 1, v14
	v_mov_b32_e32 v31, v0
	v_lshl_add_u64 v[12:13], v[12:13], 0, v[30:31]
	global_load_dwordx4 v[12:15], v[12:13], off nt
	v_lshl_add_u64 v[16:17], s[4:5], 0, v[28:29]
	v_lshl_add_u64 v[16:17], v[16:17], 0, v[30:31]
	global_load_dwordx4 v[16:19], v[16:17], off nt
	v_add_u32_e32 v1, s76, v1
	v_add_u32_e32 v10, s92, v10
	s_waitcnt vmcnt(1)
	v_and_b32_e32 v33, 0xffff0000, v15
	v_and_b32_e32 v37, 0xffff0000, v14
	v_lshlrev_b32_e32 v32, 16, v15
	v_lshlrev_b32_e32 v36, 16, v14
	v_mov_b32_e32 v38, v33
	v_mov_b32_e32 v39, v37
	v_mov_b32_e32 v14, v32
	v_mov_b32_e32 v15, v36
	v_pk_mul_f32 v[38:39], v[38:39], v[38:39]
	s_waitcnt vmcnt(0)
	v_lshlrev_b32_e32 v34, 16, v19
	v_pk_fma_f32 v[14:15], v[14:15], v[14:15], v[38:39]
	v_lshlrev_b32_e32 v38, 16, v18
	v_and_b32_e32 v39, 0xffff0000, v18
	v_mul_f32_e32 v11, 0xbfb8aa3b, v38
	v_exp_f32_e32 v18, v11
	v_mul_f32_e32 v11, 0xbfb8aa3b, v39
	v_and_b32_e32 v35, 0xffff0000, v19
	v_exp_f32_e32 v19, v11
	s_nop 0
	v_pk_add_f32 v[18:19], v[18:19], 1.0 op_sel_hi:[1,0]
	s_nop 0
	s_nop 0
	s_nop 0
	s_nop 0
	s_nop 0
	s_nop 0
	s_nop 0
	s_nop 0
	s_nop 0
	s_nop 0
	s_nop 0
	s_nop 0
	v_rcp_f32_e32 v19, v19
	s_nop 0
	s_nop 0
	s_nop 0
	s_nop 0
	s_nop 0
	s_nop 0
	s_nop 0
	s_nop 0
	s_nop 0
	s_nop 0
	s_nop 0
	v_lshlrev_b32_e32 v40, 16, v17
	v_rcp_f32_e32 v18, v18
	v_and_b32_e32 v41, 0xffff0000, v17
	v_mul_f32_e32 v11, 0xbfb8aa3b, v40
	v_exp_f32_e32 v42, v11
	v_mul_f32_e32 v11, 0xbfb8aa3b, v41
	v_exp_f32_e32 v43, v11
	v_pk_mul_f32 v[18:19], v[18:19], v[38:39]
	v_lshlrev_b32_e32 v38, 16, v13
	v_and_b32_e32 v39, 0xffff0000, v13
	v_pk_add_f32 v[42:43], v[42:43], 1.0 op_sel_hi:[1,0]
	s_nop 0
	s_nop 0
	s_nop 0
	s_nop 0
	s_nop 0
	s_nop 0
	s_nop 0
	s_nop 0
	s_nop 0
	s_nop 0
	s_nop 0
	s_nop 0
	v_rcp_f32_e32 v43, v43
	s_nop 0
	s_nop 0
	s_nop 0
	s_nop 0
	s_nop 0
	s_nop 0
	s_nop 0
	s_nop 0
	s_nop 0
	s_nop 0
	s_nop 0
	v_rcp_f32_e32 v42, v42
	s_nop 0
	v_pk_mul_f32 v[40:41], v[42:43], v[40:41]
	v_and_b32_e32 v43, 0xffff0000, v12
	v_lshlrev_b32_e32 v42, 16, v12
	v_mov_b32_e32 v44, v43
	v_mov_b32_e32 v45, v39
	v_mov_b32_e32 v12, v42
	v_mov_b32_e32 v13, v38
	v_pk_mul_f32 v[44:45], v[44:45], v[44:45]
	s_nop 0
	v_pk_fma_f32 v[12:13], v[12:13], v[12:13], v[44:45]
	v_lshlrev_b32_e32 v44, 16, v16
	v_and_b32_e32 v45, 0xffff0000, v16
	v_mul_f32_e32 v11, 0xbfb8aa3b, v44
	v_exp_f32_e32 v16, v11
	v_mul_f32_e32 v11, 0xbfb8aa3b, v45
	v_exp_f32_e32 v17, v11
	s_nop 0
	v_pk_add_f32 v[16:17], v[16:17], 1.0 op_sel_hi:[1,0]
	s_nop 0
	s_nop 0
	s_nop 0
	s_nop 0
	s_nop 0
	s_nop 0
	s_nop 0
	s_nop 0
	s_nop 0
	s_nop 0
	s_nop 0
	s_nop 0
	v_rcp_f32_e32 v17, v17
	s_nop 0
	s_nop 0
	s_nop 0
	s_nop 0
	s_nop 0
	s_nop 0
	s_nop 0
	s_nop 0
	s_nop 0
	s_nop 0
	s_nop 0
	v_rcp_f32_e32 v16, v16
	v_add_f32_e32 v11, v12, v13
	v_add_f32_e32 v11, v15, v11
	v_add_f32_e32 v11, v14, v11
	ds_bpermute_b32 v12, v2, v11
	v_pk_mul_f32 v[16:17], v[16:17], v[44:45]
	s_waitcnt lgkmcnt(0)
	v_add_f32_e32 v11, v11, v12
	ds_bpermute_b32 v12, v3, v11
	s_waitcnt lgkmcnt(0)
	v_add_f32_e32 v11, v11, v12
	ds_bpermute_b32 v12, v8, v11
	s_waitcnt lgkmcnt(0)
	v_add_f32_e32 v11, v11, v12
	ds_bpermute_b32 v12, v9, v11
	s_waitcnt lgkmcnt(0)
	v_add_f32_e32 v11, v11, v12
	v_fmamk_f32 v11, v11, 0x3c000000, v208
	v_cmp_gt_f32_e32 vcc, s51, v11
	v_mul_f32_e32 v12, 0x4b800000, v11
	s_nop 0
	v_cndmask_b32_e32 v11, v11, v12, vcc
	v_rsq_f32_e32 v11, v11
	s_nop 0
	v_mul_f32_e32 v12, 0x45800000, v11
	v_cndmask_b32_e32 v44, v11, v12, vcc
	v_pk_mul_f32 v[12:13], v[44:45], v[42:43] op_sel_hi:[0,1]
	s_waitcnt vmcnt(0)
	v_pk_mul_f32 v[12:13], v[24:25], v[12:13]
	v_mul_f32_e32 v11, 0xbfb8aa3b, v34
	v_pk_mul_f32 v[12:13], v[16:17], v[12:13]
	v_exp_f32_e32 v16, v11
	v_mul_f32_e32 v11, 0xbfb8aa3b, v35
	v_pk_mul_f32 v[14:15], v[44:45], v[38:39] op_sel_hi:[0,1]
	v_exp_f32_e32 v17, v11
	v_pk_mul_f32 v[14:15], v[26:27], v[14:15]
	v_cvt_pk_bf16_f32 v12, v12, v13
	v_pk_mul_f32 v[14:15], v[40:41], v[14:15]
	v_pk_add_f32 v[16:17], v[16:17], 1.0 op_sel_hi:[1,0]
	v_cvt_pk_bf16_f32 v13, v14, v15
	v_pk_mul_f32 v[14:15], v[44:45], v[36:37] op_sel_hi:[0,1]
	v_pk_mul_f32 v[14:15], v[20:21], v[14:15]
	s_nop 0
	v_pk_mul_f32 v[14:15], v[18:19], v[14:15]
	v_pk_mul_f32 v[18:19], v[44:45], v[32:33] op_sel_hi:[0,1]
	v_cvt_pk_bf16_f32 v14, v14, v15
	s_nop 0
	v_pk_mul_f32 v[18:19], v[22:23], v[18:19]
	s_nop 0
	s_nop 0
	s_nop 0
	s_nop 0
	s_nop 0
	s_nop 0
	s_nop 0
	s_nop 0
	v_rcp_f32_e32 v17, v17
	s_nop 0
	s_nop 0
	s_mov_b32 s10, 0x1fffff
	s_nop 0
	s_nop 0
	s_nop 0
	s_nop 0
	s_nop 0
	s_nop 0
	s_nop 0
	s_nop 0
	v_rcp_f32_e32 v16, v16
	s_nop 0
	v_pk_mul_f32 v[16:17], v[16:17], v[34:35]
	v_cmp_lt_i32_e32 vcc, s10, v1
	v_pk_mul_f32 v[16:17], v[16:17], v[18:19]
	s_or_b64 s[8:9], vcc, s[8:9]
	v_cvt_pk_bf16_f32 v15, v16, v17
	v_lshl_add_u64 v[16:17], s[6:7], 0, v[28:29]
	v_lshl_add_u64 v[16:17], v[16:17], 0, v[30:31]
	global_store_dwordx4 v[16:17], v[12:15], off nt
	s_andn2_b64 exec, exec, s[8:9]
	s_cbranch_execnz .LBB0_761
